# v20: window-attention staging loads prefetched one step ahead across the barrier; conv moved back to WG<128 half
# speedup vs baseline: 1.5106x; 1.0119x over previous
.LBB0_190:
	v_add_u32_e32 v80, v72, v98
	ds_read_b128 v[34:37], v80
	ds_read_b128 v[76:79], v80 offset:32
	v_mov_b32_e32 v85, v74
	v_add_u32_e32 v86, v71, v98
	v_add_u32_e32 v87, 0x11000, v86
	s_waitcnt vmcnt(3) lgkmcnt(1)
	v_mfma_f32_32x32x16_bf16 v[34:49], v[34:37], v[50:53], 0
	v_add_u32_e32 v88, 0x11020, v86
	v_add_u32_e32 v90, 0x15200, v86
	v_add_u32_e32 v94, 0x15220, v86
	s_add_i32 s1, s1, -1
	v_add_u32_e32 v71, 64, v71
	v_add_u32_e32 v72, 0x1200, v72
	s_cmp_eq_u32 s1, 0
	s_waitcnt vmcnt(2) lgkmcnt(0)
	v_mfma_f32_32x32x16_bf16 v[34:49], v[76:79], v[54:57], v[34:49]
	ds_read_b128 v[74:77], v80 offset:64
	ds_read_b128 v[78:81], v80 offset:96
	s_waitcnt vmcnt(1) lgkmcnt(1)
	v_mfma_f32_32x32x16_bf16 v[34:49], v[74:77], v[58:61], v[34:49]
	ds_read_b128 v[74:77], v87
	ds_read_b128 v[86:89], v88
	ds_read_b128 v[90:93], v90
	ds_read_b128 v[94:97], v94
	s_waitcnt vmcnt(0) lgkmcnt(4)
	v_mfma_f32_32x32x16_bf16 v[34:49], v[78:81], v[62:65], v[34:49]
	s_nop 11
	v_mul_f32_e32 v78, 0x3e38aa3b, v34
	v_mul_f32_e32 v79, 0x3e38aa3b, v35
	v_mul_f32_e32 v80, 0x3e38aa3b, v36
	v_mul_f32_e32 v81, 0x3e38aa3b, v37
	v_max3_f32 v78, v78, s52, v79
	v_mul_f32_e32 v103, 0x3e38aa3b, v38
	v_mul_f32_e32 v104, 0x3e38aa3b, v39
	v_max3_f32 v78, v78, v80, v81
	v_mul_f32_e32 v106, 0x3e38aa3b, v40
	v_mul_f32_e32 v107, 0x3e38aa3b, v41
	v_max3_f32 v78, v78, v103, v104
	v_mul_f32_e32 v108, 0x3e38aa3b, v42
	v_mul_f32_e32 v109, 0x3e38aa3b, v43
	v_max3_f32 v78, v78, v106, v107
	v_mul_f32_e32 v110, 0x3e38aa3b, v44
	v_mul_f32_e32 v111, 0x3e38aa3b, v45
	v_max3_f32 v78, v78, v108, v109
	v_mul_f32_e32 v112, 0x3e38aa3b, v46
	v_mul_f32_e32 v113, 0x3e38aa3b, v47
	v_max3_f32 v78, v78, v110, v111
	v_mul_f32_e32 v114, 0x3e38aa3b, v48
	v_mul_f32_e32 v115, 0x3e38aa3b, v49
	v_max3_f32 v78, v78, v112, v113
	v_max3_f32 v78, v78, v114, v115
	ds_bpermute_b32 v79, v99, v78
	s_waitcnt lgkmcnt(0)
	v_max3_f32 v78, v73, v78, v79
	v_fma_f32 v34, v34, s18, -v78
	v_sub_f32_e32 v73, v73, v78
	v_fma_f32 v35, v35, s18, -v78
	v_fma_f32 v36, v36, s18, -v78
	v_fma_f32 v37, v37, s18, -v78
	v_fma_f32 v38, v38, s18, -v78
	v_fma_f32 v39, v39, s18, -v78
	v_fma_f32 v40, v40, s18, -v78
	v_fma_f32 v41, v41, s18, -v78
	v_exp_f32_e32 v79, v34
	v_exp_f32_e32 v80, v35
	v_exp_f32_e32 v81, v36
	v_exp_f32_e32 v103, v37
	v_exp_f32_e32 v104, v38
	v_exp_f32_e32 v39, v39
	v_exp_f32_e32 v40, v40
	v_exp_f32_e32 v41, v41
	v_exp_f32_e32 v38, v73
	v_add_f32_e32 v73, 0, v79
	v_cvt_pk_bf16_f32 v34, v79, v80
	v_cvt_pk_bf16_f32 v35, v81, v103
	v_pk_mul_f32 v[32:33], v[32:33], v[38:39] op_sel_hi:[1,0]
	v_pk_mul_f32 v[30:31], v[30:31], v[38:39] op_sel_hi:[1,0]
	v_pk_mul_f32 v[28:29], v[28:29], v[38:39] op_sel_hi:[1,0]
	v_pk_mul_f32 v[26:27], v[26:27], v[38:39] op_sel_hi:[1,0]
	v_pk_mul_f32 v[24:25], v[24:25], v[38:39] op_sel_hi:[1,0]
	v_pk_mul_f32 v[22:23], v[22:23], v[38:39] op_sel_hi:[1,0]
	v_pk_mul_f32 v[20:21], v[20:21], v[38:39] op_sel_hi:[1,0]
	v_pk_mul_f32 v[18:19], v[18:19], v[38:39] op_sel_hi:[1,0]
	v_pk_mul_f32 v[16:17], v[16:17], v[38:39] op_sel_hi:[1,0]
	v_cvt_pk_bf16_f32 v36, v104, v39
	v_cvt_pk_bf16_f32 v37, v40, v41
	v_pk_mul_f32 v[14:15], v[14:15], v[38:39] op_sel_hi:[1,0]
	v_pk_mul_f32 v[12:13], v[12:13], v[38:39] op_sel_hi:[1,0]
	v_pk_mul_f32 v[10:11], v[10:11], v[38:39] op_sel_hi:[1,0]
	v_pk_mul_f32 v[8:9], v[8:9], v[38:39] op_sel_hi:[1,0]
	v_pk_mul_f32 v[6:7], v[6:7], v[38:39] op_sel_hi:[1,0]
	v_pk_mul_f32 v[4:5], v[4:5], v[38:39] op_sel_hi:[1,0]
	v_pk_mul_f32 v[2:3], v[2:3], v[38:39] op_sel_hi:[1,0]
	v_add_f32_e32 v73, v80, v73
	v_mfma_f32_32x32x16_bf16 v[18:33], v[74:77], v[34:37], v[18:33]
	v_add_f32_e32 v73, v81, v73
	v_fma_f32 v42, v42, s18, -v78
	v_add_f32_e32 v73, v103, v73
	v_fma_f32 v43, v43, s18, -v78
	v_fma_f32 v44, v44, s18, -v78
	v_fma_f32 v45, v45, s18, -v78
	v_fma_f32 v46, v46, s18, -v78
	v_mfma_f32_32x32x16_bf16 v[2:17], v[90:93], v[34:37], v[2:17]
	v_fma_f32 v47, v47, s18, -v78
	v_fma_f32 v48, v48, s18, -v78
	v_fma_f32 v49, v49, s18, -v78
	v_exp_f32_e32 v42, v42
	v_add_f32_e32 v73, v104, v73
	v_exp_f32_e32 v43, v43
	v_exp_f32_e32 v44, v44
	v_exp_f32_e32 v45, v45
	v_exp_f32_e32 v46, v46
	v_exp_f32_e32 v47, v47
	v_exp_f32_e32 v48, v48
	v_exp_f32_e32 v49, v49
	v_add_f32_e32 v39, v39, v73
	v_add_f32_e32 v39, v40, v39
	v_add_f32_e32 v39, v41, v39
	v_add_f32_e32 v39, v42, v39
	v_cvt_pk_bf16_f32 v34, v42, v43
	v_cvt_pk_bf16_f32 v35, v44, v45
	v_cvt_pk_bf16_f32 v36, v46, v47
	v_cvt_pk_bf16_f32 v37, v48, v49
	v_add_f32_e32 v39, v43, v39
	v_mov_b32_e32 v73, v78
	v_mfma_f32_32x32x16_bf16 v[18:33], v[86:89], v[34:37], v[18:33]
	v_mfma_f32_32x32x16_bf16 v[2:17], v[94:97], v[34:37], v[2:17]
	v_add_f32_e32 v34, v44, v39
	v_add_f32_e32 v34, v45, v34
	v_add_f32_e32 v34, v46, v34
	v_add_f32_e32 v34, v47, v34
	v_add_f32_e32 v34, v48, v34
	v_add_f32_e32 v34, v49, v34
	ds_bpermute_b32 v35, v99, v34
	s_waitcnt lgkmcnt(0)
	v_add_f32_e32 v74, v34, v35
	v_fmac_f32_e32 v74, v85, v38
	s_cbranch_scc0 .LBB0_190
	s_and_b64 s[12:13], s[4:5], exec
	s_movk_i32 s1, 0x1a00
	s_cselect_b32 s12, 0x1200, s1
	s_mov_b32 s13, s31
	v_lshl_add_u64 v[34:35], v[68:69], 0, s[12:13]
	s_lshl_b64 s[12:13], s[30:31], 1
	v_lshl_add_u64 v[36:37], v[34:35], 0, s[12:13]
	v_lshlrev_b64 v[34:35], 11, v[66:67]
	s_and_b64 s[4:5], s[4:5], exec
	s_movk_i32 s1, 0x600
	v_lshl_add_u64 v[34:35], s[8:9], 0, v[34:35]
	s_cselect_b32 s30, 0x400, s1
	v_lshl_add_u64 v[34:35], v[34:35], 0, s[30:31]
	v_lshl_add_u64 v[38:39], v[34:35], 0, s[12:13]
	v_div_scale_f32 v34, s[4:5], v74, v74, 1.0
	v_rcp_f32_e32 v35, v34
	v_mov_b32_e32 v103, v1
	v_lshl_add_u64 v[36:37], v[36:37], 0, v[102:103]
	s_lshl_b32 s2, s58, 8
	v_fma_f32 v40, -v34, v35, 1.0
	v_fmac_f32_e32 v35, v40, v35
	v_div_scale_f32 v40, vcc, 1.0, v74, 1.0
	v_mul_f32_e32 v41, v40, v35
	v_fma_f32 v42, -v34, v41, v40
	v_fmac_f32_e32 v41, v42, v35
	v_fma_f32 v34, -v34, v41, v40
	v_div_fmas_f32 v34, v34, v35, v41
	global_load_dwordx2 v[40:41], v[36:37], off
	v_div_fixup_f32 v34, v34, v74, 1.0
	s_ashr_i32 s13, s58, 6
	s_bfe_u32 s1, s58, 0x20004
	s_lshl_b32 s30, s1, 7
	v_readlane_b32 s44, v255, 20
	v_readlane_b32 s45, v255, 21
	s_mov_b64 s[22:23], s[44:45]
	v_readlane_b32 s46, v255, 22
	v_readlane_b32 s47, v255, 23
	v_readlane_b32 s48, v255, 24
	v_readlane_b32 s49, v255, 25
	v_readlane_b32 s50, v255, 26
	v_readlane_b32 s51, v255, 27
	s_waitcnt vmcnt(0)
	v_lshlrev_b32_e32 v35, 16, v40
	v_and_b32_e32 v40, 0xffff0000, v40
	v_mul_f32_e32 v42, 0xbfb8aa3b, v35
	v_mul_f32_e32 v43, 0xbfb8aa3b, v40
	v_exp_f32_e32 v42, v42
	v_exp_f32_e32 v43, v43
	v_pk_mul_f32 v[18:19], v[18:19], v[34:35] op_sel_hi:[1,0]
	v_pk_add_f32 v[42:43], v[42:43], 1.0 op_sel_hi:[1,0]
	s_nop 0
	v_div_scale_f32 v44, s[4:5], v43, v43, v40
	v_rcp_f32_e32 v45, v44
	s_nop 0
	v_fma_f32 v46, -v44, v45, 1.0
	v_fmac_f32_e32 v45, v46, v45
	v_div_scale_f32 v46, vcc, v40, v43, v40
	v_mul_f32_e32 v47, v46, v45
	v_fma_f32 v48, -v44, v47, v46
	v_fmac_f32_e32 v47, v48, v45
	v_fma_f32 v44, -v44, v47, v46
	v_div_fmas_f32 v44, v44, v45, v47
	v_div_fixup_f32 v43, v44, v43, v40
	v_div_scale_f32 v40, s[4:5], v42, v42, v35
	v_rcp_f32_e32 v44, v40
	s_nop 0
	v_fma_f32 v45, -v40, v44, 1.0
	v_fmac_f32_e32 v44, v45, v44
	v_div_scale_f32 v45, vcc, v35, v42, v35
	v_mul_f32_e32 v46, v45, v44
	v_fma_f32 v47, -v40, v46, v45
	v_fmac_f32_e32 v46, v47, v44
	v_fma_f32 v40, -v40, v46, v45
	v_div_fmas_f32 v40, v40, v44, v46
	v_div_fixup_f32 v42, v40, v42, v35
	v_pk_mul_f32 v[18:19], v[18:19], v[42:43]
	v_lshlrev_b32_e32 v35, 16, v41
	v_and_b32_e32 v42, 0xffff0000, v41
	v_mul_f32_e32 v40, 0xbfb8aa3b, v35
	v_mul_f32_e32 v41, 0xbfb8aa3b, v42
	v_exp_f32_e32 v40, v40
	v_exp_f32_e32 v41, v41
	v_pk_mul_f32 v[20:21], v[20:21], v[34:35] op_sel_hi:[1,0]
	v_pk_add_f32 v[40:41], v[40:41], 1.0 op_sel_hi:[1,0]
	s_nop 0
	v_div_scale_f32 v43, s[4:5], v41, v41, v42
	v_rcp_f32_e32 v44, v43
	s_nop 0
	v_fma_f32 v45, -v43, v44, 1.0
	v_fmac_f32_e32 v44, v45, v44
	v_div_scale_f32 v45, vcc, v42, v41, v42
	v_mul_f32_e32 v46, v45, v44
	v_fma_f32 v47, -v43, v46, v45
	v_fmac_f32_e32 v46, v47, v44
	v_fma_f32 v43, -v43, v46, v45
	v_div_fmas_f32 v43, v43, v44, v46
	v_div_fixup_f32 v41, v43, v41, v42
	v_div_scale_f32 v42, s[4:5], v40, v40, v35
	v_rcp_f32_e32 v43, v42
	s_nop 0
	v_fma_f32 v44, -v42, v43, 1.0
	v_fmac_f32_e32 v43, v44, v43
	v_div_scale_f32 v44, vcc, v35, v40, v35
	v_mul_f32_e32 v45, v44, v43
	v_fma_f32 v46, -v42, v45, v44
	v_fmac_f32_e32 v45, v46, v43
	v_fma_f32 v42, -v42, v45, v44
	v_div_fmas_f32 v42, v42, v43, v45
	v_div_fixup_f32 v40, v42, v40, v35
	v_pk_mul_f32 v[40:41], v[20:21], v[40:41]
	v_cvt_pk_bf16_f32 v20, v18, v19
	v_cvt_pk_bf16_f32 v21, v40, v41
	v_lshl_add_u64 v[18:19], v[38:39], 0, v[102:103]
	global_store_dwordx2 v[18:19], v[20:21], off
	global_load_dwordx2 v[38:39], v[36:37], off offset:16
	s_waitcnt vmcnt(0)
	v_lshlrev_b32_e32 v35, 16, v38
	v_and_b32_e32 v38, 0xffff0000, v38
	v_mul_f32_e32 v20, 0xbfb8aa3b, v35
	v_mul_f32_e32 v21, 0xbfb8aa3b, v38
	v_exp_f32_e32 v20, v20
	v_exp_f32_e32 v21, v21
	v_pk_mul_f32 v[22:23], v[22:23], v[34:35] op_sel_hi:[1,0]
	v_pk_add_f32 v[20:21], v[20:21], 1.0 op_sel_hi:[1,0]
	s_nop 0
	v_div_scale_f32 v40, s[4:5], v21, v21, v38
	v_rcp_f32_e32 v41, v40
	s_nop 0
	v_fma_f32 v42, -v40, v41, 1.0
	v_fmac_f32_e32 v41, v42, v41
	v_div_scale_f32 v42, vcc, v38, v21, v38
	v_mul_f32_e32 v43, v42, v41
	v_fma_f32 v44, -v40, v43, v42
	v_fmac_f32_e32 v43, v44, v41
	v_fma_f32 v40, -v40, v43, v42
	v_div_fmas_f32 v40, v40, v41, v43
	v_div_fixup_f32 v21, v40, v21, v38
	v_div_scale_f32 v38, s[4:5], v20, v20, v35
	v_rcp_f32_e32 v40, v38
	s_nop 0
	v_fma_f32 v41, -v38, v40, 1.0
	v_fmac_f32_e32 v40, v41, v40
	v_div_scale_f32 v41, vcc, v35, v20, v35
	v_mul_f32_e32 v42, v41, v40
	v_fma_f32 v43, -v38, v42, v41
	v_fmac_f32_e32 v42, v43, v40
	v_fma_f32 v38, -v38, v42, v41
	v_div_fmas_f32 v38, v38, v40, v42
	v_div_fixup_f32 v20, v38, v20, v35
	v_lshlrev_b32_e32 v35, 16, v39
	v_pk_mul_f32 v[20:21], v[22:23], v[20:21]
	v_and_b32_e32 v40, 0xffff0000, v39
	v_mul_f32_e32 v22, 0xbfb8aa3b, v35
	v_exp_f32_e32 v38, v22
	v_pk_mul_f32 v[22:23], v[24:25], v[34:35] op_sel_hi:[1,0]
	v_mul_f32_e32 v24, 0xbfb8aa3b, v40
	v_exp_f32_e32 v39, v24
	v_cvt_pk_bf16_f32 v20, v20, v21
	v_pk_add_f32 v[24:25], v[38:39], 1.0 op_sel_hi:[1,0]
	s_nop 0
	v_div_scale_f32 v38, s[4:5], v25, v25, v40
	v_rcp_f32_e32 v39, v38
	s_nop 0
	v_fma_f32 v41, -v38, v39, 1.0
	v_fmac_f32_e32 v39, v41, v39
	v_div_scale_f32 v41, vcc, v40, v25, v40
	v_mul_f32_e32 v42, v41, v39
	v_fma_f32 v43, -v38, v42, v41
	v_fmac_f32_e32 v42, v43, v39
	v_fma_f32 v38, -v38, v42, v41
	v_div_fmas_f32 v38, v38, v39, v42
	v_div_fixup_f32 v25, v38, v25, v40
	v_div_scale_f32 v38, s[4:5], v24, v24, v35
	v_rcp_f32_e32 v39, v38
	s_nop 0
	v_fma_f32 v40, -v38, v39, 1.0
	v_fmac_f32_e32 v39, v40, v39
	v_div_scale_f32 v40, vcc, v35, v24, v35
	v_mul_f32_e32 v41, v40, v39
	v_fma_f32 v42, -v38, v41, v40
	v_fmac_f32_e32 v41, v42, v39
	v_fma_f32 v38, -v38, v41, v40
	v_div_fmas_f32 v38, v38, v39, v41
	v_div_fixup_f32 v24, v38, v24, v35
	v_pk_mul_f32 v[22:23], v[22:23], v[24:25]
	s_nop 0
	v_cvt_pk_bf16_f32 v21, v22, v23
	global_store_dwordx2 v[18:19], v[20:21], off offset:16
	global_load_dwordx2 v[22:23], v[36:37], off offset:32
	s_waitcnt vmcnt(0)
	v_lshlrev_b32_e32 v35, 16, v22
	v_and_b32_e32 v22, 0xffff0000, v22
	v_mul_f32_e32 v20, 0xbfb8aa3b, v35
	v_mul_f32_e32 v21, 0xbfb8aa3b, v22
	v_exp_f32_e32 v20, v20
	v_exp_f32_e32 v21, v21
	v_pk_mul_f32 v[24:25], v[26:27], v[34:35] op_sel_hi:[1,0]
	v_pk_add_f32 v[20:21], v[20:21], 1.0 op_sel_hi:[1,0]
	s_nop 0
	v_div_scale_f32 v26, s[4:5], v21, v21, v22
	v_rcp_f32_e32 v27, v26
	s_nop 0
	v_fma_f32 v38, -v26, v27, 1.0
	v_fmac_f32_e32 v27, v38, v27
	v_div_scale_f32 v38, vcc, v22, v21, v22
	v_mul_f32_e32 v39, v38, v27
	v_fma_f32 v40, -v26, v39, v38
	v_fmac_f32_e32 v39, v40, v27
	v_fma_f32 v26, -v26, v39, v38
	v_div_fmas_f32 v26, v26, v27, v39
	v_div_fixup_f32 v21, v26, v21, v22
	v_div_scale_f32 v22, s[4:5], v20, v20, v35
	v_rcp_f32_e32 v26, v22
	s_nop 0
	v_fma_f32 v27, -v22, v26, 1.0
	v_fmac_f32_e32 v26, v27, v26
	v_div_scale_f32 v27, vcc, v35, v20, v35
	v_mul_f32_e32 v38, v27, v26
	v_fma_f32 v39, -v22, v38, v27
	v_fmac_f32_e32 v38, v39, v26
	v_fma_f32 v22, -v22, v38, v27
	v_div_fmas_f32 v22, v22, v26, v38
	v_div_fixup_f32 v20, v22, v20, v35
	v_lshlrev_b32_e32 v26, 16, v23
	v_and_b32_e32 v27, 0xffff0000, v23
	v_pk_mul_f32 v[20:21], v[24:25], v[20:21]
	v_mul_f32_e32 v22, 0xbfb8aa3b, v26
	v_mul_f32_e32 v25, 0xbfb8aa3b, v27
	v_exp_f32_e32 v24, v22
	v_exp_f32_e32 v25, v25
	v_pk_mul_f32 v[22:23], v[28:29], v[34:35] op_sel_hi:[1,0]
	v_cvt_pk_bf16_f32 v20, v20, v21
	v_pk_add_f32 v[24:25], v[24:25], 1.0 op_sel_hi:[1,0]
	s_nop 0
	v_div_scale_f32 v28, s[4:5], v25, v25, v27
	v_rcp_f32_e32 v29, v28
	s_nop 0
	v_fma_f32 v35, -v28, v29, 1.0
	v_fmac_f32_e32 v29, v35, v29
	v_div_scale_f32 v35, vcc, v27, v25, v27
	v_mul_f32_e32 v38, v35, v29
	v_fma_f32 v39, -v28, v38, v35
	v_fmac_f32_e32 v38, v39, v29
	v_fma_f32 v28, -v28, v38, v35
	v_div_fmas_f32 v28, v28, v29, v38
	v_div_fixup_f32 v25, v28, v25, v27
	v_div_scale_f32 v27, s[4:5], v24, v24, v26
	v_rcp_f32_e32 v28, v27
	s_nop 0
	v_fma_f32 v29, -v27, v28, 1.0
	v_fmac_f32_e32 v28, v29, v28
	v_div_scale_f32 v29, vcc, v26, v24, v26
	v_mul_f32_e32 v35, v29, v28
	v_fma_f32 v38, -v27, v35, v29
	v_fmac_f32_e32 v35, v38, v28
	v_fma_f32 v27, -v27, v35, v29
	v_div_fmas_f32 v27, v27, v28, v35
	v_div_fixup_f32 v24, v27, v24, v26
	v_pk_mul_f32 v[22:23], v[22:23], v[24:25]
	v_pk_mul_f32 v[24:25], v[30:31], v[34:35] op_sel_hi:[1,0]
	v_cvt_pk_bf16_f32 v21, v22, v23
	global_store_dwordx2 v[18:19], v[20:21], off offset:32
	global_load_dwordx2 v[22:23], v[36:37], off offset:48
	v_pk_mul_f32 v[2:3], v[2:3], v[34:35] op_sel_hi:[1,0]
	v_pk_mul_f32 v[4:5], v[4:5], v[34:35] op_sel_hi:[1,0]
	v_pk_mul_f32 v[6:7], v[6:7], v[34:35] op_sel_hi:[1,0]
	s_waitcnt vmcnt(0)
	v_lshlrev_b32_e32 v26, 16, v22
	v_and_b32_e32 v22, 0xffff0000, v22
	v_mul_f32_e32 v20, 0xbfb8aa3b, v26
	v_mul_f32_e32 v21, 0xbfb8aa3b, v22
	v_exp_f32_e32 v20, v20
	v_exp_f32_e32 v21, v21
	s_nop 0
	v_pk_add_f32 v[20:21], v[20:21], 1.0 op_sel_hi:[1,0]
	s_nop 0
	v_div_scale_f32 v27, s[4:5], v21, v21, v22
	v_rcp_f32_e32 v28, v27
	s_nop 0
	v_fma_f32 v29, -v27, v28, 1.0
	v_fmac_f32_e32 v28, v29, v28
	v_div_scale_f32 v29, vcc, v22, v21, v22
	v_mul_f32_e32 v30, v29, v28
	v_fma_f32 v31, -v27, v30, v29
	v_fmac_f32_e32 v30, v31, v28
	v_fma_f32 v27, -v27, v30, v29
	v_div_fmas_f32 v27, v27, v28, v30
	v_div_fixup_f32 v21, v27, v21, v22
	v_div_scale_f32 v22, s[4:5], v20, v20, v26
	v_rcp_f32_e32 v27, v22
	s_nop 0
	v_fma_f32 v28, -v22, v27, 1.0
	v_fmac_f32_e32 v27, v28, v27
	v_div_scale_f32 v28, vcc, v26, v20, v26
	v_mul_f32_e32 v29, v28, v27
	v_fma_f32 v30, -v22, v29, v28
	v_fmac_f32_e32 v29, v30, v27
	v_fma_f32 v22, -v22, v29, v28
	v_div_fmas_f32 v22, v22, v27, v29
	v_div_fixup_f32 v20, v22, v20, v26
	v_lshlrev_b32_e32 v26, 16, v23
	v_and_b32_e32 v27, 0xffff0000, v23
	v_pk_mul_f32 v[20:21], v[24:25], v[20:21]
	v_mul_f32_e32 v22, 0xbfb8aa3b, v26
	v_mul_f32_e32 v25, 0xbfb8aa3b, v27
	v_exp_f32_e32 v24, v22
	v_exp_f32_e32 v25, v25
	v_pk_mul_f32 v[22:23], v[32:33], v[34:35] op_sel_hi:[1,0]
	v_cvt_pk_bf16_f32 v20, v20, v21
	v_pk_add_f32 v[24:25], v[24:25], 1.0 op_sel_hi:[1,0]
	s_nop 0
	v_div_scale_f32 v28, s[4:5], v25, v25, v27
	v_rcp_f32_e32 v29, v28
	s_nop 0
	v_fma_f32 v30, -v28, v29, 1.0
	v_fmac_f32_e32 v29, v30, v29
	v_div_scale_f32 v30, vcc, v27, v25, v27
	v_mul_f32_e32 v31, v30, v29
	v_fma_f32 v32, -v28, v31, v30
	v_fmac_f32_e32 v31, v32, v29
	v_fma_f32 v28, -v28, v31, v30
	v_div_fmas_f32 v28, v28, v29, v31
	v_div_fixup_f32 v25, v28, v25, v27
	v_div_scale_f32 v27, s[4:5], v24, v24, v26
	v_rcp_f32_e32 v28, v27
	s_nop 0
	v_fma_f32 v29, -v27, v28, 1.0
	v_fmac_f32_e32 v28, v29, v28
	v_div_scale_f32 v29, vcc, v26, v24, v26
	v_mul_f32_e32 v30, v29, v28
	v_fma_f32 v31, -v27, v30, v29
	v_fmac_f32_e32 v30, v31, v28
	v_fma_f32 v27, -v27, v30, v29
	v_div_fmas_f32 v27, v27, v28, v30
	v_div_fixup_f32 v24, v27, v24, v26
	v_pk_mul_f32 v[22:23], v[22:23], v[24:25]
	s_nop 0
	v_cvt_pk_bf16_f32 v21, v22, v23
	global_store_dwordx2 v[18:19], v[20:21], off offset:48
	global_load_dwordx2 v[20:21], v[36:37], off offset:64
	s_waitcnt vmcnt(0)
	v_lshlrev_b32_e32 v24, 16, v20
	v_and_b32_e32 v20, 0xffff0000, v20
	v_mul_f32_e32 v22, 0xbfb8aa3b, v24
	v_mul_f32_e32 v23, 0xbfb8aa3b, v20
	v_exp_f32_e32 v22, v22
	v_exp_f32_e32 v23, v23
	s_nop 0
	v_pk_add_f32 v[22:23], v[22:23], 1.0 op_sel_hi:[1,0]
	s_nop 0
	v_div_scale_f32 v25, s[4:5], v23, v23, v20
	v_rcp_f32_e32 v26, v25
	s_nop 0
	v_fma_f32 v27, -v25, v26, 1.0
	v_fmac_f32_e32 v26, v27, v26
	v_div_scale_f32 v27, vcc, v20, v23, v20
	v_mul_f32_e32 v28, v27, v26
	v_fma_f32 v29, -v25, v28, v27
	v_fmac_f32_e32 v28, v29, v26
	v_fma_f32 v25, -v25, v28, v27
	v_div_fmas_f32 v25, v25, v26, v28
	v_div_fixup_f32 v23, v25, v23, v20
	v_div_scale_f32 v20, s[4:5], v22, v22, v24
	v_rcp_f32_e32 v25, v20
	s_nop 0
	v_fma_f32 v26, -v20, v25, 1.0
	v_fmac_f32_e32 v25, v26, v25
	v_div_scale_f32 v26, vcc, v24, v22, v24
	v_mul_f32_e32 v27, v26, v25
	v_fma_f32 v28, -v20, v27, v26
	v_fmac_f32_e32 v27, v28, v25
	v_fma_f32 v20, -v20, v27, v26
	v_div_fmas_f32 v20, v20, v25, v27
	v_div_fixup_f32 v22, v20, v22, v24
	v_pk_mul_f32 v[2:3], v[2:3], v[22:23]
	v_lshlrev_b32_e32 v22, 16, v21
	v_and_b32_e32 v23, 0xffff0000, v21
	v_mul_f32_e32 v20, 0xbfb8aa3b, v22
	v_mul_f32_e32 v21, 0xbfb8aa3b, v23
	v_exp_f32_e32 v20, v20
	v_exp_f32_e32 v21, v21
	v_cvt_pk_bf16_f32 v2, v2, v3
	v_pk_add_f32 v[20:21], v[20:21], 1.0 op_sel_hi:[1,0]
	s_nop 0
	v_div_scale_f32 v24, s[4:5], v21, v21, v23
	v_rcp_f32_e32 v25, v24
	s_nop 0
	v_fma_f32 v26, -v24, v25, 1.0
	v_fmac_f32_e32 v25, v26, v25
	v_div_scale_f32 v26, vcc, v23, v21, v23
	v_mul_f32_e32 v27, v26, v25
	v_fma_f32 v28, -v24, v27, v26
	v_fmac_f32_e32 v27, v28, v25
	v_fma_f32 v24, -v24, v27, v26
	v_div_fmas_f32 v24, v24, v25, v27
	v_div_fixup_f32 v21, v24, v21, v23
	v_div_scale_f32 v23, s[4:5], v20, v20, v22
	v_rcp_f32_e32 v24, v23
	s_nop 0
	v_fma_f32 v25, -v23, v24, 1.0
	v_fmac_f32_e32 v24, v25, v24
	v_div_scale_f32 v25, vcc, v22, v20, v22
	v_mul_f32_e32 v26, v25, v24
	v_fma_f32 v27, -v23, v26, v25
	v_fmac_f32_e32 v26, v27, v24
	v_fma_f32 v23, -v23, v26, v25
	v_div_fmas_f32 v23, v23, v24, v26
	v_div_fixup_f32 v20, v23, v20, v22
	v_pk_mul_f32 v[4:5], v[4:5], v[20:21]
	s_nop 0
	v_cvt_pk_bf16_f32 v3, v4, v5
	global_store_dwordx2 v[18:19], v[2:3], off offset:64
	global_load_dwordx2 v[4:5], v[36:37], off offset:80
	s_waitcnt vmcnt(0)
	v_lshlrev_b32_e32 v20, 16, v4
	v_and_b32_e32 v4, 0xffff0000, v4
	v_mul_f32_e32 v2, 0xbfb8aa3b, v20
	v_mul_f32_e32 v3, 0xbfb8aa3b, v4
	v_exp_f32_e32 v2, v2
	v_exp_f32_e32 v3, v3
	s_nop 0
	v_pk_add_f32 v[2:3], v[2:3], 1.0 op_sel_hi:[1,0]
	s_nop 0
	v_div_scale_f32 v21, s[4:5], v3, v3, v4
	v_rcp_f32_e32 v22, v21
	s_nop 0
	v_fma_f32 v23, -v21, v22, 1.0
	v_fmac_f32_e32 v22, v23, v22
	v_div_scale_f32 v23, vcc, v4, v3, v4
	v_mul_f32_e32 v24, v23, v22
	v_fma_f32 v25, -v21, v24, v23
	v_fmac_f32_e32 v24, v25, v22
	v_fma_f32 v21, -v21, v24, v23
	v_div_fmas_f32 v21, v21, v22, v24
	v_div_fixup_f32 v3, v21, v3, v4
	v_div_scale_f32 v4, s[4:5], v2, v2, v20
	v_rcp_f32_e32 v21, v4
	s_nop 0
	v_fma_f32 v22, -v4, v21, 1.0
	v_fmac_f32_e32 v21, v22, v21
	v_div_scale_f32 v22, vcc, v20, v2, v20
	v_mul_f32_e32 v23, v22, v21
	v_fma_f32 v24, -v4, v23, v22
	v_fmac_f32_e32 v23, v24, v21
	v_fma_f32 v4, -v4, v23, v22
	v_div_fmas_f32 v4, v4, v21, v23
	v_div_fixup_f32 v2, v4, v2, v20
	v_lshlrev_b32_e32 v20, 16, v5
	v_and_b32_e32 v21, 0xffff0000, v5
	v_pk_mul_f32 v[2:3], v[6:7], v[2:3]
	v_mul_f32_e32 v4, 0xbfb8aa3b, v20
	v_mul_f32_e32 v7, 0xbfb8aa3b, v21
	v_exp_f32_e32 v6, v4
	v_exp_f32_e32 v7, v7
	v_pk_mul_f32 v[4:5], v[8:9], v[34:35] op_sel_hi:[1,0]
	v_cvt_pk_bf16_f32 v2, v2, v3
	v_pk_add_f32 v[6:7], v[6:7], 1.0 op_sel_hi:[1,0]
	s_nop 0
	v_div_scale_f32 v8, s[4:5], v7, v7, v21
	v_rcp_f32_e32 v9, v8
	s_nop 0
	v_fma_f32 v22, -v8, v9, 1.0
	v_fmac_f32_e32 v9, v22, v9
	v_div_scale_f32 v22, vcc, v21, v7, v21
	v_mul_f32_e32 v23, v22, v9
	v_fma_f32 v24, -v8, v23, v22
	v_fmac_f32_e32 v23, v24, v9
	v_fma_f32 v8, -v8, v23, v22
	v_div_fmas_f32 v8, v8, v9, v23
	v_div_fixup_f32 v7, v8, v7, v21
	v_div_scale_f32 v8, s[4:5], v6, v6, v20
	v_rcp_f32_e32 v9, v8
	s_nop 0
	v_fma_f32 v21, -v8, v9, 1.0
	v_fmac_f32_e32 v9, v21, v9
	v_div_scale_f32 v21, vcc, v20, v6, v20
	v_mul_f32_e32 v22, v21, v9
	v_fma_f32 v23, -v8, v22, v21
	v_fmac_f32_e32 v22, v23, v9
	v_fma_f32 v8, -v8, v22, v21
	v_div_fmas_f32 v8, v8, v9, v22
	v_div_fixup_f32 v6, v8, v6, v20
	v_pk_mul_f32 v[4:5], v[4:5], v[6:7]
	v_pk_mul_f32 v[6:7], v[10:11], v[34:35] op_sel_hi:[1,0]
	v_cvt_pk_bf16_f32 v3, v4, v5
	global_store_dwordx2 v[18:19], v[2:3], off offset:80
	global_load_dwordx2 v[4:5], v[36:37], off offset:96
	s_waitcnt vmcnt(0)
	v_lshlrev_b32_e32 v8, 16, v4
	v_and_b32_e32 v4, 0xffff0000, v4
	v_mul_f32_e32 v2, 0xbfb8aa3b, v8
	v_mul_f32_e32 v3, 0xbfb8aa3b, v4
	v_exp_f32_e32 v2, v2
	v_exp_f32_e32 v3, v3
	s_nop 0
	v_pk_add_f32 v[2:3], v[2:3], 1.0 op_sel_hi:[1,0]
	s_nop 0
	v_div_scale_f32 v9, s[4:5], v3, v3, v4
	v_rcp_f32_e32 v10, v9
	s_nop 0
	v_fma_f32 v11, -v9, v10, 1.0
	v_fmac_f32_e32 v10, v11, v10
	v_div_scale_f32 v11, vcc, v4, v3, v4
	v_mul_f32_e32 v20, v11, v10
	v_fma_f32 v21, -v9, v20, v11
	v_fmac_f32_e32 v20, v21, v10
	v_fma_f32 v9, -v9, v20, v11
	v_div_fmas_f32 v9, v9, v10, v20
	v_div_fixup_f32 v3, v9, v3, v4
	v_div_scale_f32 v4, s[4:5], v2, v2, v8
	v_rcp_f32_e32 v9, v4
	s_nop 0
	v_fma_f32 v10, -v4, v9, 1.0
	v_fmac_f32_e32 v9, v10, v9
	v_div_scale_f32 v10, vcc, v8, v2, v8
	v_mul_f32_e32 v11, v10, v9
	v_fma_f32 v20, -v4, v11, v10
	v_fmac_f32_e32 v11, v20, v9
	v_fma_f32 v4, -v4, v11, v10
	v_div_fmas_f32 v4, v4, v9, v11
	v_div_fixup_f32 v2, v4, v2, v8
	v_lshlrev_b32_e32 v8, 16, v5
	v_and_b32_e32 v9, 0xffff0000, v5
	v_pk_mul_f32 v[2:3], v[6:7], v[2:3]
	v_mul_f32_e32 v4, 0xbfb8aa3b, v8
	v_mul_f32_e32 v7, 0xbfb8aa3b, v9
	v_exp_f32_e32 v6, v4
	v_exp_f32_e32 v7, v7
	v_pk_mul_f32 v[4:5], v[12:13], v[34:35] op_sel_hi:[1,0]
	v_cvt_pk_bf16_f32 v2, v2, v3
	v_pk_add_f32 v[6:7], v[6:7], 1.0 op_sel_hi:[1,0]
	s_nop 0
	v_div_scale_f32 v10, s[4:5], v7, v7, v9
	v_rcp_f32_e32 v11, v10
	s_nop 0
	v_fma_f32 v12, -v10, v11, 1.0
	v_fmac_f32_e32 v11, v12, v11
	v_div_scale_f32 v12, vcc, v9, v7, v9
	v_mul_f32_e32 v13, v12, v11
	v_fma_f32 v20, -v10, v13, v12
	v_fmac_f32_e32 v13, v20, v11
	v_fma_f32 v10, -v10, v13, v12
	v_div_fmas_f32 v10, v10, v11, v13
	v_div_fixup_f32 v7, v10, v7, v9
	v_div_scale_f32 v9, s[4:5], v6, v6, v8
	v_rcp_f32_e32 v10, v9
	s_nop 0
	v_fma_f32 v11, -v9, v10, 1.0
	v_fmac_f32_e32 v10, v11, v10
	v_div_scale_f32 v11, vcc, v8, v6, v8
	v_mul_f32_e32 v12, v11, v10
	v_fma_f32 v13, -v9, v12, v11
	v_fmac_f32_e32 v12, v13, v10
	v_fma_f32 v9, -v9, v12, v11
	v_div_fmas_f32 v9, v9, v10, v12
	v_div_fixup_f32 v6, v9, v6, v8
	v_pk_mul_f32 v[4:5], v[4:5], v[6:7]
	v_pk_mul_f32 v[6:7], v[14:15], v[34:35] op_sel_hi:[1,0]
	v_cvt_pk_bf16_f32 v3, v4, v5
	global_store_dwordx2 v[18:19], v[2:3], off offset:96
	global_load_dwordx2 v[2:3], v[36:37], off offset:112
	s_waitcnt vmcnt(0)
	v_lshlrev_b32_e32 v8, 16, v2
	v_and_b32_e32 v2, 0xffff0000, v2
	v_mul_f32_e32 v4, 0xbfb8aa3b, v8
	v_mul_f32_e32 v5, 0xbfb8aa3b, v2
	v_exp_f32_e32 v4, v4
	v_exp_f32_e32 v5, v5
	s_nop 0
	v_pk_add_f32 v[4:5], v[4:5], 1.0 op_sel_hi:[1,0]
	s_nop 0
	v_div_scale_f32 v9, s[4:5], v5, v5, v2
	v_rcp_f32_e32 v10, v9
	s_nop 0
	v_fma_f32 v11, -v9, v10, 1.0
	v_fmac_f32_e32 v10, v11, v10
	v_div_scale_f32 v11, vcc, v2, v5, v2
	v_mul_f32_e32 v12, v11, v10
	v_fma_f32 v13, -v9, v12, v11
	v_fmac_f32_e32 v12, v13, v10
	v_fma_f32 v9, -v9, v12, v11
	v_div_fmas_f32 v9, v9, v10, v12
	v_div_fixup_f32 v5, v9, v5, v2
	v_div_scale_f32 v2, s[4:5], v4, v4, v8
	v_rcp_f32_e32 v9, v2
	s_nop 0
	v_fma_f32 v10, -v2, v9, 1.0
	v_fmac_f32_e32 v9, v10, v9
	v_div_scale_f32 v10, vcc, v8, v4, v8
	v_mul_f32_e32 v11, v10, v9
	v_fma_f32 v12, -v2, v11, v10
	v_fmac_f32_e32 v11, v12, v9
	v_fma_f32 v2, -v2, v11, v10
	v_div_fmas_f32 v2, v2, v9, v11
	v_div_fixup_f32 v4, v2, v4, v8
	v_lshlrev_b32_e32 v8, 16, v3
	v_and_b32_e32 v9, 0xffff0000, v3
	v_mul_f32_e32 v2, 0xbfb8aa3b, v8
	v_mul_f32_e32 v3, 0xbfb8aa3b, v9
	v_exp_f32_e32 v2, v2
	v_exp_f32_e32 v3, v3
	v_pk_mul_f32 v[4:5], v[6:7], v[4:5]
	v_pk_mul_f32 v[6:7], v[16:17], v[34:35] op_sel_hi:[1,0]
	v_cvt_pk_bf16_f32 v4, v4, v5
	v_pk_add_f32 v[2:3], v[2:3], 1.0 op_sel_hi:[1,0]
	s_nop 0
	v_div_scale_f32 v10, s[4:5], v3, v3, v9
	v_rcp_f32_e32 v11, v10
	s_nop 0
	v_fma_f32 v12, -v10, v11, 1.0
	v_fmac_f32_e32 v11, v12, v11
	v_div_scale_f32 v12, vcc, v9, v3, v9
	v_mul_f32_e32 v13, v12, v11
	v_fma_f32 v14, -v10, v13, v12
	v_fmac_f32_e32 v13, v14, v11
	v_fma_f32 v10, -v10, v13, v12
	v_div_fmas_f32 v10, v10, v11, v13
	v_div_fixup_f32 v3, v10, v3, v9
	v_div_scale_f32 v9, s[4:5], v2, v2, v8
	v_rcp_f32_e32 v10, v9
	s_and_b32 s4, s2, 0xf00
	s_lshl_b32 s2, s13, 12
	s_addk_i32 s2, 0x1000
	v_fma_f32 v11, -v9, v10, 1.0
	v_fmac_f32_e32 v10, v11, v10
	v_div_scale_f32 v11, vcc, v8, v2, v8
	v_mul_f32_e32 v12, v11, v10
	v_fma_f32 v13, -v9, v12, v11
	v_fmac_f32_e32 v12, v13, v10
	v_fma_f32 v9, -v9, v12, v11
	v_div_fmas_f32 v9, v9, v10, v12
	v_div_fixup_f32 v2, v9, v2, v8
	v_pk_mul_f32 v[2:3], v[6:7], v[2:3]
	v_lshlrev_b32_e32 v6, 1, v102
	v_cvt_pk_bf16_f32 v5, v2, v3
	global_store_dwordx2 v[18:19], v[4:5], off offset:112
	v_add_u32_e32 v5, s4, v70
	v_or_b32_e32 v4, v5, v124
	v_add_u32_e32 v104, s2, v4
	v_mov_b64_e32 v[2:3], s[6:7]
	v_mad_i64_i32 v[106:107], s[20:21], v104, s19, v[2:3]
	v_lshl_add_u64 v[2:3], v[106:107], 0, s[30:31]
	v_mov_b32_e32 v7, v1
	v_lshl_add_u64 v[2:3], v[2:3], 0, v[6:7]
	s_barrier
	global_load_dwordx4 v[66:69], v[2:3], off offset:3584
	global_load_dwordx4 v[70:73], v[2:3], off offset:3616
	global_load_dwordx4 v[74:77], v[2:3], off offset:3648
	global_load_dwordx4 v[78:81], v[2:3], off offset:3680
	s_max_u32 s12, s4, 0x80
	s_min_u32 s4, s4, 0xe80
	s_sub_i32 s4, s4, s12
	s_addk_i32 s4, 0x200
	s_ashr_i32 s5, s4, 7
	s_cmp_gt_i32 s5, -4
	s_cbranch_scc0 .LBB0_211
	s_lshr_b32 s4, s4, 7
	s_lshr_b32 s30, s1, 1
	s_add_i32 s17, s4, 4
	s_lshl_b32 s4, s30, 6
	s_lshl_b32 s5, s13, 7
	s_or_b32 s4, s4, s5
	s_ashr_i32 s5, s4, 31
	s_lshl_b64 s[4:5], s[4:5], 13
	s_add_u32 s4, s76, s4
	s_addc_u32 s5, s77, s5
	s_lshl_b32 s13, s13, 3
	s_lshl_b32 s20, s34, 1
	s_add_i32 s13, s13, s20
	s_or_b32 s20, s13, s30
	s_ashr_i32 s21, s20, 31
	s_lshl_b64 s[20:21], s[20:21], 16
	s_mul_hi_i32 s13, s2, 0x1c00
	s_mulk_i32 s2, 0x1c00
	s_add_u32 s2, s6, s2
	s_addc_u32 s13, s7, s13
	s_lshl_b32 s30, s30, 7
	s_add_u32 s36, s2, s30
	s_addc_u32 s37, s13, 0
	s_add_u32 s20, s76, s20
	s_mov_b32 s79, s31
	s_addc_u32 s21, s77, s21
	s_lshl_b64 s[44:45], s[78:79], 2
	s_add_u32 s22, s22, s44
	s_addc_u32 s23, s23, s45
	s_lshl_b32 s2, s1, 2
	v_mov_b32_e32 v2, s2
	global_load_dword v22, v2, s[22:23]
	v_ashrrev_i32_e32 v18, 4, v100
	v_and_b32_e32 v16, 0xf0, v82
	v_mov_b32_e32 v17, v1
	v_ashrrev_i32_e32 v19, 31, v18
	s_movk_i32 s2, 0x110
	v_mul_lo_u32 v25, v18, s2
	v_lshlrev_b64 v[108:109], 13, v[18:19]
	v_lshlrev_b64 v[110:111], 10, v[18:19]
	v_lshl_add_u64 v[18:19], s[4:5], 0, v[16:17]
	s_mov_b64 s[4:5], 0xda00000
	v_lshl_add_u64 v[116:117], v[18:19], 0, s[4:5]
	v_lshl_add_u64 v[18:19], s[36:37], 0, v[0:1]
	v_ashrrev_i32_e32 v20, 4, v83
	v_mov_b32_e32 v14, v1
	v_mov_b32_e32 v15, v1
	v_lshl_add_u64 v[118:119], v[18:19], 0, s[24:25]
	v_lshl_add_u64 v[18:19], s[20:21], 0, v[0:1]
	s_mov_b64 s[4:5], 0xe200000
	v_add_u32_e32 v103, 0xffffff80, v5
	v_add_u32_e32 v129, 0x9f, v5
	v_add_u32_e32 v134, 0xffffff80, v4
	v_add_u32_e32 v135, 0x80, v4
	v_mul_u32_u24_e32 v23, 0x110, v124
	v_mov_b32_e32 v2, v1
	v_mov_b32_e32 v3, v1
	v_mov_b32_e32 v4, v1
	v_mov_b32_e32 v5, v1
	v_mov_b32_e32 v6, v1
	v_mov_b32_e32 v7, v1
	v_mov_b32_e32 v8, v1
	v_mov_b32_e32 v9, v1
	v_mov_b32_e32 v10, v1
	v_mov_b32_e32 v11, v1
	v_mov_b32_e32 v12, v1
	v_mov_b32_e32 v13, v1
	v_add_u32_e32 v24, 0, v16
	v_ashrrev_i32_e32 v21, 31, v20
	v_mul_lo_u32 v26, v20, s2
	v_readlane_b32 s2, v255, 36
	v_lshl_add_u64 v[16:17], s[20:21], 0, v[16:17]
	v_mov_b32_e32 v0, v1
	v_lshl_add_u64 v[120:121], v[18:19], 0, s[4:5]
	s_mov_b64 s[4:5], 0xe300000
	v_mov_b64_e32 v[64:65], v[14:15]
	v_mov_b64_e32 v[48:49], v[14:15]
	v_add3_u32 v136, v84, v98, s0
	v_mov_b32_e32 v140, 1.0
	s_mov_b32 s0, 0
	v_add3_u32 v137, v23, v98, s2
	s_sext_i32_i16 s2, s17
	v_lshlrev_b64 v[112:113], 13, v[20:21]
	v_lshlrev_b64 v[114:115], 10, v[20:21]
	v_add_u32_e32 v138, v24, v25
	v_add_u32_e32 v139, v24, v26
	s_addk_i32 s12, 0xfd80
	v_lshl_add_u64 v[122:123], v[16:17], 0, s[4:5]
	v_mov_b64_e32 v[62:63], v[12:13]
	v_mov_b64_e32 v[60:61], v[10:11]
	v_mov_b64_e32 v[58:59], v[8:9]
	v_mov_b64_e32 v[56:57], v[6:7]
	v_mov_b64_e32 v[54:55], v[4:5]
	v_mov_b64_e32 v[52:53], v[2:3]
	v_mov_b64_e32 v[50:51], v[0:1]
	v_mov_b64_e32 v[46:47], v[12:13]
	v_mov_b64_e32 v[44:45], v[10:11]
	v_mov_b64_e32 v[42:43], v[8:9]
	v_mov_b64_e32 v[40:41], v[6:7]
	v_mov_b64_e32 v[38:39], v[4:5]
	v_mov_b64_e32 v[36:37], v[2:3]
	v_mov_b64_e32 v[34:35], v[0:1]
	s_waitcnt vmcnt(0)
	v_mul_f32_e32 v143, 0x3fb8aa3b, v22
	v_lshlrev_b32_e32 v228, 7, v105
	v_add_u32_e32 v196, v228, v120
	v_subrev_u32_e32 v196, s56, v196
	v_lshlrev_b32_e32 v228, 7, v127
	v_add_u32_e32 v198, v228, v120
	v_subrev_u32_e32 v198, s56, v198
	v_add_u32_e32 v197, v122, v110
	v_subrev_u32_e32 v197, s56, v197
	v_add_u32_e32 v199, v122, v114
	v_subrev_u32_e32 v199, s56, v199
	s_add_i32 s4, s12, 0x200
	v_add_u32_e32 v228, s4, v105
	v_mul_u32_u24_e32 v228, 0x1c00, v228
	v_add_u32_e32 v200, v228, v118
	v_subrev_u32_e32 v200, s56, v200
	v_add_u32_e32 v228, s4, v127
	v_mul_u32_u24_e32 v228, 0x1c00, v228
	v_add_u32_e32 v202, v228, v118
	v_subrev_u32_e32 v202, s56, v202
	s_lshl_b32 s4, s4, 1
	v_add_u32_e32 v201, v116, v108
	v_add_u32_e32 v201, s4, v201
	v_subrev_u32_e32 v201, s56, v201
	v_add_u32_e32 v203, v116, v112
	v_add_u32_e32 v203, s4, v203
	v_subrev_u32_e32 v203, s56, v203
	global_load_dwordx4 v[204:207], v196, s[56:57]
	global_load_dwordx4 v[208:211], v197, s[56:57]
	global_load_dwordx4 v[212:215], v198, s[56:57]
	global_load_dwordx4 v[216:219], v199, s[56:57]
	v_add_u32_e32 v196, 0x4000, v196
	v_add_u32_e32 v198, 0x4000, v198
	v_add_u32_e32 v197, 0x100, v197
	v_add_u32_e32 v199, 0x100, v199
.LBB0_193:
	s_cmp_gt_u32 s0, 3
	s_cselect_b64 s[80:81], -1, 0
	s_lshl_b32 s30, s0, 7
	s_add_i32 s82, s12, s30
	s_cmp_lt_u32 s0, 4
	s_cselect_b32 s82, s30, s82
	s_ashr_i32 s83, s82, 31
	s_waitcnt vmcnt(0)
	ds_write_b128 v126, v[204:207] offset:32768
	ds_write_b128 v138, v[208:211] offset:51200
	ds_write_b128 v128, v[212:215] offset:32768
	ds_write_b128 v139, v[216:219] offset:51200
	v_add_u32_e32 v0, s82, v102
	s_mov_b32 s13, 0
	v_mov_b32_e32 v141, v137
	v_mov_b32_e32 v142, v136
	s_waitcnt lgkmcnt(0)
	s_barrier
	s_add_i32 s4, s0, 1
	s_cmp_ge_u32 s4, s2
	s_cbranch_scc1 .Lwin_pf_done
	s_cmp_lt_u32 s4, 4
	s_cbranch_scc0 .Lwin_pf_lat
	global_load_dwordx4 v[204:207], v196, s[56:57]
	global_load_dwordx4 v[208:211], v197, s[56:57]
	global_load_dwordx4 v[212:215], v198, s[56:57]
	global_load_dwordx4 v[216:219], v199, s[56:57]
	v_add_u32_e32 v196, 0x4000, v196
	v_add_u32_e32 v198, 0x4000, v198
	v_add_u32_e32 v197, 0x100, v197
	v_add_u32_e32 v199, 0x100, v199
	s_branch .Lwin_pf_done
.Lwin_pf_lat:
	global_load_dwordx4 v[204:207], v200, s[56:57]
	global_load_dwordx4 v[208:211], v201, s[56:57]
	global_load_dwordx4 v[212:215], v202, s[56:57]
	global_load_dwordx4 v[216:219], v203, s[56:57]
	v_add_u32_e32 v200, 0xe0000, v200
	v_add_u32_e32 v202, 0xe0000, v202
	v_add_u32_e32 v201, 0x100, v201
	v_add_u32_e32 v203, 0x100, v203
.Lwin_pf_done:
	s_mov_b64 s[4:5], -1
	s_and_b64 vcc, exec, s[80:81]
	s_cbranch_vccz .LBB0_206
	s_branch .LBB0_203
